# retention weight transposes (ret_w_in, ret_w_out f32->bf16) done by idle scan waves via register transpose; skipped in the prologue on a 256-workgroup grid
# speedup vs baseline: 1.0819x; 1.0023x over previous
; __device__ __forceinline__ void phase_prologue(KP P, const Ctx& c) {
;     ...
;     tr_job(c, rot, P->in[I_RETWIN], D, 16384, 16384, (bf16_t*)(ws + WS_RETIN), D, 0);
;     tr_job(c, rot, P->in[I_RETWOUT], 4096, D, D, (bf16_t*)(ws + WS_RETOUT), 4096, 0);
.LBB0_85:
	s_cmpk_lg_i32 s3, 0x100
	s_cbranch_scc1 .Lpro_keep_ret
	s_waitcnt vmcnt(0) lgkmcnt(0)
	s_branch .LBB0_95

; #define LAS __attribute__((address_space(3)))
; #define TR_LOAD(it_) do { const int kb_ = (it_) / nblk, nb_ = (it_) % nblk; _Pragma("unroll") for (int i = 0; i < 8; ++i) r[i] = *(const f32x4*)(W + (size_t)(kb_ * 64 + 8 * i + (lane >> 3)) * ldw + nb_ * 32 + (lane & 7) * 4); } while (0)
; __device__ __forceinline__ void tr_job(const Ctx& c, int& rot, const float* W, int K, int N, int ldw, bf16_t* WT, int ldt, int row_off) {
;     LAS float* scr = (LAS float*)(c.lds + c.wave * 16384);
;     const int nblk = N / 32, items = (K / 64) * nblk;
;     int first = c.gw - (rot % c.ngw); if (first < 0) first += c.ngw;
;     int lane = c.lane; asm volatile("" : "+v"(lane));
;     f32x4 r[8];
;     ...
;     if (first < items) TR_LOAD(first);
;     for (int it = first; it < items; it += c.ngw) { const int kb = it / nblk, nb = it % nblk;
; #pragma unroll
;         for (int i = 0; i < 8; ++i) { LAS float* d = scr + (8 * i + (lane >> 3)) * 33 + (lane & 7) * 4; d[0] = r[i][0]; d[1] = r[i][1]; d[2] = r[i][2]; d[3] = r[i][3]; }
;         if (it + c.ngw < items) TR_LOAD(it + c.ngw);
; __device__ __forceinline__ void phase_prologue(KP P, const Ctx& c) {
;     ...
;     tr_job(c, rot, P->in[I_RETWIN], D, 16384, 16384, (bf16_t*)(ws + WS_RETIN), D, 0);
;     tr_job(c, rot, P->in[I_RETWOUT], 4096, D, D, (bf16_t*)(ws + WS_RETOUT), 4096, 0);
.Lrw_tr:
	s_cmp_ge_u32 s8, 10
	s_cbranch_scc1 .Lrw_bonus
	s_lshr_b32 s61, s63, 6
	s_sub_i32 s61, s61, 4
	s_lshl_b32 s62, s2, 2
	s_add_i32 s61, s61, s62
	s_lshl_b32 s62, s8, 10
	s_add_i32 s61, s61, s62
	s_load_dwordx4 s[64:67], s[94:95], 0x118
	s_load_dwordx2 s[68:69], s[94:95], 0x130
	v_and_b32_e32 v102, 63, v0
	v_lshlrev_b32_e32 v103, 2, v102
	s_cmp_lt_u32 s61, 0x2000
	s_cbranch_scc0 .Lrw_tr_b
	s_lshr_b32 s71, s61, 8
	s_and_b32 s72, s61, 0xff
	s_mov_b32 s70, 0x10000
	v_lshlrev_b32_e32 v104, 12, v102
	s_waitcnt lgkmcnt(0)
	s_lshl_b32 s73, s71, 22
	s_lshl_b32 s76, s72, 8
	s_add_i32 s73, s73, s76
	s_add_u32 s64, s64, s73
	s_addc_u32 s65, s65, 0
	s_lshl_b32 s73, s72, 18
	s_lshl_b32 s76, s71, 7
	s_add_i32 s73, s73, s76
	s_add_i32 s73, s73, 0xa800000
	s_add_u32 s74, s68, s73
	s_addc_u32 s75, s69, 0
	s_branch .Lrw_tr_go
.Lrw_tr_b:
	s_sub_i32 s61, s61, 0x2000
	s_lshr_b32 s71, s61, 5
	s_and_b32 s72, s61, 31
	s_mov_b32 s70, 0x2000
	v_lshlrev_b32_e32 v104, 13, v102
	s_waitcnt lgkmcnt(0)
	s_lshl_b32 s73, s71, 19
	s_lshl_b32 s76, s72, 8
	s_add_i32 s73, s73, s76
	s_add_u32 s64, s66, s73
	s_addc_u32 s65, s67, 0
	s_lshl_b32 s73, s72, 19
	s_lshl_b32 s76, s71, 7
	s_add_i32 s73, s73, s76
	s_add_i32 s73, s73, 0xe800000
	s_add_u32 s74, s68, s73
	s_addc_u32 s75, s69, 0
.Lrw_tr_go:
	global_load_dword v38, v103, s[64:65]
	s_add_u32 s64, s64, s70
	s_addc_u32 s65, s65, 0
	global_load_dword v39, v103, s[64:65]
	s_add_u32 s64, s64, s70
	s_addc_u32 s65, s65, 0
	global_load_dword v40, v103, s[64:65]
	s_add_u32 s64, s64, s70
	s_addc_u32 s65, s65, 0
	global_load_dword v41, v103, s[64:65]
	s_add_u32 s64, s64, s70
	s_addc_u32 s65, s65, 0
	global_load_dword v42, v103, s[64:65]
	s_add_u32 s64, s64, s70
	s_addc_u32 s65, s65, 0
	global_load_dword v43, v103, s[64:65]
	s_add_u32 s64, s64, s70
	s_addc_u32 s65, s65, 0
	global_load_dword v44, v103, s[64:65]
	s_add_u32 s64, s64, s70
	s_addc_u32 s65, s65, 0
	global_load_dword v45, v103, s[64:65]
	s_add_u32 s64, s64, s70
	s_addc_u32 s65, s65, 0
	global_load_dword v46, v103, s[64:65]
	s_add_u32 s64, s64, s70
	s_addc_u32 s65, s65, 0
	global_load_dword v47, v103, s[64:65]
	s_add_u32 s64, s64, s70
	s_addc_u32 s65, s65, 0
	global_load_dword v48, v103, s[64:65]
	s_add_u32 s64, s64, s70
	s_addc_u32 s65, s65, 0
	global_load_dword v49, v103, s[64:65]
	s_add_u32 s64, s64, s70
	s_addc_u32 s65, s65, 0
	global_load_dword v50, v103, s[64:65]
	s_add_u32 s64, s64, s70
	s_addc_u32 s65, s65, 0
	global_load_dword v51, v103, s[64:65]
	s_add_u32 s64, s64, s70
	s_addc_u32 s65, s65, 0
	global_load_dword v52, v103, s[64:65]
	s_add_u32 s64, s64, s70
	s_addc_u32 s65, s65, 0
	global_load_dword v53, v103, s[64:65]
	s_add_u32 s64, s64, s70
	s_addc_u32 s65, s65, 0
	global_load_dword v54, v103, s[64:65]
	s_add_u32 s64, s64, s70
	s_addc_u32 s65, s65, 0
	global_load_dword v55, v103, s[64:65]
	s_add_u32 s64, s64, s70
	s_addc_u32 s65, s65, 0
	global_load_dword v56, v103, s[64:65]
	s_add_u32 s64, s64, s70
	s_addc_u32 s65, s65, 0
	global_load_dword v57, v103, s[64:65]
	s_add_u32 s64, s64, s70
	s_addc_u32 s65, s65, 0
	global_load_dword v58, v103, s[64:65]
	s_add_u32 s64, s64, s70
	s_addc_u32 s65, s65, 0
	global_load_dword v59, v103, s[64:65]
	s_add_u32 s64, s64, s70
	s_addc_u32 s65, s65, 0
	global_load_dword v60, v103, s[64:65]
	s_add_u32 s64, s64, s70
	s_addc_u32 s65, s65, 0
	global_load_dword v61, v103, s[64:65]
	s_add_u32 s64, s64, s70
	s_addc_u32 s65, s65, 0
	global_load_dword v62, v103, s[64:65]
	s_add_u32 s64, s64, s70
	s_addc_u32 s65, s65, 0
	global_load_dword v63, v103, s[64:65]
	s_add_u32 s64, s64, s70
	s_addc_u32 s65, s65, 0
	global_load_dword v64, v103, s[64:65]
	s_add_u32 s64, s64, s70
	s_addc_u32 s65, s65, 0
	global_load_dword v65, v103, s[64:65]
	s_add_u32 s64, s64, s70
	s_addc_u32 s65, s65, 0
	global_load_dword v66, v103, s[64:65]
	s_add_u32 s64, s64, s70
	s_addc_u32 s65, s65, 0
	global_load_dword v67, v103, s[64:65]
	s_add_u32 s64, s64, s70
	s_addc_u32 s65, s65, 0
	global_load_dword v68, v103, s[64:65]
	s_add_u32 s64, s64, s70
	s_addc_u32 s65, s65, 0
	global_load_dword v69, v103, s[64:65]
	s_add_u32 s64, s64, s70
	s_addc_u32 s65, s65, 0
	global_load_dword v70, v103, s[64:65]
	s_add_u32 s64, s64, s70
	s_addc_u32 s65, s65, 0
	global_load_dword v71, v103, s[64:65]
	s_add_u32 s64, s64, s70
	s_addc_u32 s65, s65, 0
	global_load_dword v72, v103, s[64:65]
	s_add_u32 s64, s64, s70
	s_addc_u32 s65, s65, 0
	global_load_dword v73, v103, s[64:65]
	s_add_u32 s64, s64, s70
	s_addc_u32 s65, s65, 0
	global_load_dword v74, v103, s[64:65]
	s_add_u32 s64, s64, s70
	s_addc_u32 s65, s65, 0
	global_load_dword v75, v103, s[64:65]
	s_add_u32 s64, s64, s70
	s_addc_u32 s65, s65, 0
	global_load_dword v76, v103, s[64:65]
	s_add_u32 s64, s64, s70
	s_addc_u32 s65, s65, 0
	global_load_dword v77, v103, s[64:65]
	s_add_u32 s64, s64, s70
	s_addc_u32 s65, s65, 0
	global_load_dword v78, v103, s[64:65]
	s_add_u32 s64, s64, s70
	s_addc_u32 s65, s65, 0
	global_load_dword v79, v103, s[64:65]
	s_add_u32 s64, s64, s70
	s_addc_u32 s65, s65, 0
	global_load_dword v80, v103, s[64:65]
	s_add_u32 s64, s64, s70
	s_addc_u32 s65, s65, 0
	global_load_dword v81, v103, s[64:65]
	s_add_u32 s64, s64, s70
	s_addc_u32 s65, s65, 0
	global_load_dword v82, v103, s[64:65]
	s_add_u32 s64, s64, s70
	s_addc_u32 s65, s65, 0
	global_load_dword v83, v103, s[64:65]
	s_add_u32 s64, s64, s70
	s_addc_u32 s65, s65, 0
	global_load_dword v84, v103, s[64:65]
	s_add_u32 s64, s64, s70
	s_addc_u32 s65, s65, 0
	global_load_dword v85, v103, s[64:65]
	s_add_u32 s64, s64, s70
	s_addc_u32 s65, s65, 0
	global_load_dword v86, v103, s[64:65]
	s_add_u32 s64, s64, s70
	s_addc_u32 s65, s65, 0
	global_load_dword v87, v103, s[64:65]
	s_add_u32 s64, s64, s70
	s_addc_u32 s65, s65, 0
	global_load_dword v88, v103, s[64:65]
	s_add_u32 s64, s64, s70
	s_addc_u32 s65, s65, 0
	global_load_dword v89, v103, s[64:65]
	s_add_u32 s64, s64, s70
	s_addc_u32 s65, s65, 0
	global_load_dword v90, v103, s[64:65]
	s_add_u32 s64, s64, s70
	s_addc_u32 s65, s65, 0
	global_load_dword v91, v103, s[64:65]
	s_add_u32 s64, s64, s70
	s_addc_u32 s65, s65, 0
	global_load_dword v92, v103, s[64:65]
	s_add_u32 s64, s64, s70
	s_addc_u32 s65, s65, 0
	global_load_dword v93, v103, s[64:65]
	s_add_u32 s64, s64, s70
	s_addc_u32 s65, s65, 0
	global_load_dword v94, v103, s[64:65]
	s_add_u32 s64, s64, s70
	s_addc_u32 s65, s65, 0
	global_load_dword v95, v103, s[64:65]
	s_add_u32 s64, s64, s70
	s_addc_u32 s65, s65, 0
	global_load_dword v96, v103, s[64:65]
	s_add_u32 s64, s64, s70
	s_addc_u32 s65, s65, 0
	global_load_dword v97, v103, s[64:65]
	s_add_u32 s64, s64, s70
	s_addc_u32 s65, s65, 0
	global_load_dword v98, v103, s[64:65]
	s_add_u32 s64, s64, s70
	s_addc_u32 s65, s65, 0
	global_load_dword v99, v103, s[64:65]
	s_add_u32 s64, s64, s70
	s_addc_u32 s65, s65, 0
	global_load_dword v100, v103, s[64:65]
	s_add_u32 s64, s64, s70
	s_addc_u32 s65, s65, 0
	global_load_dword v101, v103, s[64:65]
	s_waitcnt vmcnt(0)
; #define LAS __attribute__((address_space(3)))
; __device__ __forceinline__ void tr_job(const Ctx& c, int& rot, const float* W, int K, int N, int ldw, bf16_t* WT, int ldt, int row_off) {
;     ...
;         const int cc = lane & 7;
; #pragma unroll
;         for (int j = 0; j < 4; ++j) { const int n = (lane >> 3) + 8 * j; const LAS float* sp = scr + (8 * cc) * 33 + n;
;             u32x4 o; o.x = cvt_pk_bf16(sp[0 * 33], sp[1 * 33]); o.y = cvt_pk_bf16(sp[2 * 33], sp[3 * 33]); o.z = cvt_pk_bf16(sp[4 * 33], sp[5 * 33]); o.w = cvt_pk_bf16(sp[6 * 33], sp[7 * 33]);
;             *(u32x4*)(WT + (size_t)(row_off + nb * 32 + n) * ldt + kb * 64 + 8 * cc) = o; }
	v_cvt_pk_bf16_f32 v170, v38, v39
	v_cvt_pk_bf16_f32 v171, v40, v41
	v_cvt_pk_bf16_f32 v172, v42, v43
	v_cvt_pk_bf16_f32 v173, v44, v45
	v_cvt_pk_bf16_f32 v174, v46, v47
	v_cvt_pk_bf16_f32 v175, v48, v49
	v_cvt_pk_bf16_f32 v176, v50, v51
	v_cvt_pk_bf16_f32 v177, v52, v53
	v_cvt_pk_bf16_f32 v178, v54, v55
	v_cvt_pk_bf16_f32 v179, v56, v57
	v_cvt_pk_bf16_f32 v180, v58, v59
	v_cvt_pk_bf16_f32 v181, v60, v61
	v_cvt_pk_bf16_f32 v182, v62, v63
	v_cvt_pk_bf16_f32 v183, v64, v65
	v_cvt_pk_bf16_f32 v184, v66, v67
	v_cvt_pk_bf16_f32 v185, v68, v69
	v_cvt_pk_bf16_f32 v186, v70, v71
	v_cvt_pk_bf16_f32 v187, v72, v73
	v_cvt_pk_bf16_f32 v188, v74, v75
	v_cvt_pk_bf16_f32 v189, v76, v77
	v_cvt_pk_bf16_f32 v190, v78, v79
	v_cvt_pk_bf16_f32 v191, v80, v81
	v_cvt_pk_bf16_f32 v192, v82, v83
	v_cvt_pk_bf16_f32 v193, v84, v85
	v_cvt_pk_bf16_f32 v194, v86, v87
	v_cvt_pk_bf16_f32 v195, v88, v89
	v_cvt_pk_bf16_f32 v196, v90, v91
	v_cvt_pk_bf16_f32 v197, v92, v93
	v_cvt_pk_bf16_f32 v198, v94, v95
	v_cvt_pk_bf16_f32 v199, v96, v97
	v_cvt_pk_bf16_f32 v200, v98, v99
	v_cvt_pk_bf16_f32 v201, v100, v101
	global_store_dwordx4 v104, v[170:173], s[74:75]
	global_store_dwordx4 v104, v[174:177], s[74:75] offset:16
	global_store_dwordx4 v104, v[178:181], s[74:75] offset:32
	global_store_dwordx4 v104, v[182:185], s[74:75] offset:48
	global_store_dwordx4 v104, v[186:189], s[74:75] offset:64
	global_store_dwordx4 v104, v[190:193], s[74:75] offset:80
	global_store_dwordx4 v104, v[194:197], s[74:75] offset:96
	global_store_dwordx4 v104, v[198:201], s[74:75] offset:112
	s_branch .Lrw_bonus
